# strategy 8 extended: counted lgkmcnt(12/8/4) before the S=K.Q MFMA groups of the selected-attention tile loop
# baseline (speedup 1.0000x reference)
; __device__ __forceinline__ void tile_dma(unsigned char* lds, int slot, const bf16_t* Kg, const bf16_t* Vtg, int kb, int tid) {
;     unsigned char* kd = lds + slot * RING_SLOT; unsigned char* vd = kd + RING_V;
; #pragma unroll
;     for (int i = 0; i < 2; ++i) {
;         const int q = i * 512 + tid;
;         { const int rs = q >> 4, pos = q & 15, c = pos ^ (rs & 15), nt = rs >> 4, r16 = rs & 15;
;           const int keyl = 32 * (nt >> 1) + 8 * (r16 >> 2) + 4 * (nt & 1) + (r16 & 3);
;           __builtin_amdgcn_global_load_lds((const unsigned*)(Kg + ((size_t)kb * 64 + keyl) * 128 + c * 8),
;                                            (__attribute__((address_space(3))) unsigned*)(kd + q * 16), 16, 0, 0); }
;         { const int d = q >> 3, pos = q & 7, c = pos ^ ((d >> 1) & 7);
;           __builtin_amdgcn_global_load_lds((const unsigned*)(Vtg + (size_t)d * SEQ + kb * 64 + c * 8),
;                                            (__attribute__((address_space(3))) unsigned*)(vd + q * 16), 16, 0, 0); }
;     }
; template <int MODE>
; __device__ __forceinline__ void attn_compute(const bf16x8 (&qf)[4], const unsigned char* Ks, const unsigned char* Vs, int kb, int tok,
;                                              unsigned long long msk, f32x4 (&O)[8], float& mrow, float& lrow) {
;     ...
;     if (MODE == 1) {
;         if (__builtin_amdgcn_ballot_w64(((msk >> kb) & 1ull) != 0ull) == 0ull) return;
;     }
;     f32x4 S[4];
;     {
;         bf16x8 kf[16];
; #pragma unroll
;         for (int i = 0; i < 16; ++i) kf[i] = *(const bf16x8*)(Ks + ((i >> 2) * 16 + fr) * 256 + ((((i & 3) * 4 + fq) ^ fr) * 16));
;         __builtin_amdgcn_sched_barrier(0);
; #pragma unroll
;         for (int nt = 0; nt < 4; ++nt) {
;             S[nt] = zero4();
; #pragma unroll
;             for (int ks = 0; ks < 4; ++ks) S[nt] = mfma16(kf[nt * 4 + ks], qf[ks], S[nt]);
;         }
;     }
;     bf16x8 vf[16];
; #pragma unroll
;     for (int i = 0; i < 16; ++i) vf[i] = *(const bf16x8*)(Vs + ((i & 7) * 16 + fr) * 128 + ((((i >> 3) * 4 + fq) ^ ((fr >> 1) & 7)) * 16));
;     const bool rowok = (MODE == 0) ? true : (((msk >> kb) & 1ull) != 0ull);
;     const int key0 = kb * 64 + 8 * fq;
;     const int tb = __builtin_amdgcn_readfirstlane(tok - fr);
;     const bool interior = (kb * 64 + 63 <= tb) && (MODE == 1 || kb * 64 > tb + 15 - 512);
;     float mx = -1e30f;
;     if (interior) {
.LBB0_209:
	s_cmp_eq_u64 s[46:47], 0
	s_ff1_i32_b64 s49, s[46:47]
	s_cselect_b32 s15, s15, s49
	s_cmp_gt_i32 s45, 0
	s_cselect_b32 s49, -1, 2
	s_add_i32 s49, s49, s45
	s_lshl_b32 s49, s49, 15
	s_add_i32 s49, s49, 0
	s_lshl_b32 s92, s15, 6
	v_lshl_add_u64 v[34:35], s[92:93], 0, v[150:151]
	v_add_u32_e32 v36, s49, v145
	v_lshlrev_b64 v[34:35], 8, v[34:35]
	v_readfirstlane_b32 s50, v36
	v_add_u32_e32 v36, 0x4000, v36
	s_waitcnt vmcnt(4)
	s_barrier
	v_lshl_add_u64 v[32:33], s[92:93], 1, v[158:159]
	v_lshl_add_u64 v[34:35], v[160:161], 0, v[34:35]
	s_mov_b32 m0, s50
	v_readfirstlane_b32 s50, v36
	global_load_lds_dwordx4 v[34:35], off
	v_lshl_add_u64 v[34:35], v[32:33], 0, v[152:153]
	s_mov_b32 m0, s50
	v_add_u32_e32 v36, s49, v165
	global_load_lds_dwordx4 v[34:35], off
	v_lshl_add_u64 v[34:35], s[92:93], 0, v[154:155]
	v_lshlrev_b64 v[34:35], 8, v[34:35]
	v_readfirstlane_b32 s49, v36
	v_lshl_add_u64 v[34:35], v[162:163], 0, v[34:35]
	s_mov_b32 m0, s49
	v_lshl_add_u64 v[32:33], v[32:33], 0, v[156:157]
	global_load_lds_dwordx4 v[34:35], off
	v_add_u32_e32 v34, 0x4000, v36
	s_nop 0
	v_readfirstlane_b32 s49, v34
	s_mov_b32 m0, s49
	s_ff1_i32_b64 s49, s[42:43]
	global_load_lds_dwordx4 v[32:33], off
	v_lshrrev_b64 v[34:35], s49, v[148:149]
	v_and_b32_e32 v33, 1, v34
	v_mov_b32_e32 v32, v224
	v_cmp_eq_u32_e64 s[50:51], 1, v33
	v_cmp_ne_u32_e32 vcc, 0, v33
	s_cbranch_vccz .LBB0_208
	s_lshl_b32 s53, s45, 15
	v_lshrrev_b32_e32 v46, 4, v32
	v_bfe_u32 v169, v32, 4, 2
	v_and_b32_e32 v47, 15, v32
	s_add_i32 s53, s53, 0
	v_bitop3_b32 v34, v46, v47, 3 bitop3:0x6c
	v_bitop3_b32 v35, v169, v47, 4 bitop3:0x36
	v_bitop3_b32 v42, v169, v47, 8 bitop3:0x36
	v_bitop3_b32 v43, v169, v47, 12 bitop3:0x36
	v_lshl_add_u32 v33, v47, 8, s53
	v_lshlrev_b32_e32 v100, 4, v34
	v_lshlrev_b32_e32 v101, 4, v35
	v_lshlrev_b32_e32 v104, 4, v42
	v_lshlrev_b32_e32 v105, 4, v43
	v_add_u32_e32 v34, v33, v100
	v_add_u32_e32 v38, v33, v101
	v_add_u32_e32 v42, v33, v104
	v_add_u32_e32 v33, v33, v105
	v_or_b32_e32 v108, 16, v47
	ds_read_b128 v[34:37], v34
	ds_read_b128 v[38:41], v38
	ds_read_b128 v[42:45], v42
	ds_read_b128 v[64:67], v33
	v_lshl_add_u32 v33, v108, 8, s53
	v_add_u32_e32 v68, v33, v100
	v_add_u32_e32 v72, v33, v101
	v_add_u32_e32 v76, v33, v104
	v_add_u32_e32 v33, v33, v105
	v_or_b32_e32 v109, 32, v47
	ds_read_b128 v[68:71], v68
	ds_read_b128 v[72:75], v72
	ds_read_b128 v[76:79], v76
	ds_read_b128 v[80:83], v33
	v_lshl_add_u32 v33, v109, 8, s53
	v_add_u32_e32 v84, v33, v100
	v_add_u32_e32 v88, v33, v101
	v_add_u32_e32 v92, v33, v104
	v_add_u32_e32 v33, v33, v105
	v_or_b32_e32 v110, 48, v47
	ds_read_b128 v[84:87], v84
	ds_read_b128 v[88:91], v88
	ds_read_b128 v[92:95], v92
	ds_read_b128 v[96:99], v33
	v_lshl_add_u32 v33, v110, 8, s53
	v_add_u32_e32 v100, v33, v100
	v_add_u32_e32 v104, v33, v104
	v_add_u32_e32 v106, v33, v101
	ds_read_b128 v[100:103], v100
	ds_read_b128 v[112:115], v106
	v_add_u32_e32 v33, v33, v105
	ds_read_b128 v[128:131], v104
	ds_read_b128 v[170:173], v33
	s_mov_b32 s54, s93
	s_mov_b32 s55, s93
	v_mov_b32_e32 v104, s54
	v_mov_b32_e32 v105, s54
	v_mov_b32_e32 v106, s54
	v_mov_b32_e32 v107, s54
	s_mov_b32 s54, s93
	s_lshl_b32 s49, s49, 6
	s_waitcnt lgkmcnt(12)
	v_mfma_f32_16x16x32_bf16 v[34:37], v[34:37], v[48:51], v[104:107]
	v_mfma_f32_16x16x32_bf16 v[34:37], v[38:41], v[52:55], v[34:37]
	v_mov_b32_e32 v38, s54
	v_mov_b32_e32 v39, s54
	v_mov_b32_e32 v40, s54
	v_mfma_f32_16x16x32_bf16 v[34:37], v[42:45], v[56:59], v[34:37]
	v_mov_b32_e32 v41, s54
	s_mov_b32 s54, s93
	v_mfma_f32_16x16x32_bf16 v[132:135], v[64:67], v[60:63], v[34:37]
	v_lshl_add_u32 v65, v110, 7, s53
	v_mov_b32_e32 v42, s54
	v_mov_b32_e32 v43, s54
	s_waitcnt lgkmcnt(8)
	v_mfma_f32_16x16x32_bf16 v[34:37], v[68:71], v[48:51], v[38:41]
	v_mov_b32_e32 v44, s54
	v_mov_b32_e32 v45, s54
	s_or_b32 s54, s49, 63
	v_mfma_f32_16x16x32_bf16 v[34:37], v[72:75], v[52:55], v[34:37]
	v_mov_b32_e32 v38, s55
	v_mov_b32_e32 v39, s55
	v_mov_b32_e32 v40, s55
	v_mfma_f32_16x16x32_bf16 v[34:37], v[76:79], v[56:59], v[34:37]
	v_mov_b32_e32 v41, s55
	v_mfma_f32_16x16x32_bf16 v[136:139], v[80:83], v[60:63], v[34:37]
	s_nop 5
	v_bfe_u32 v36, v32, 1, 3
	s_waitcnt lgkmcnt(4)
	v_mfma_f32_16x16x32_bf16 v[32:35], v[84:87], v[48:51], v[38:41]
	v_lshl_add_u32 v37, v47, 7, s53
	v_mfma_f32_16x16x32_bf16 v[32:35], v[88:91], v[52:55], v[32:35]
	s_nop 0
	v_bitop3_b32 v38, v46, v36, 3 bitop3:0x6c
	v_lshlrev_b32_e32 v38, 4, v38
	v_lshl_add_u32 v46, v109, 7, s53
	v_mfma_f32_16x16x32_bf16 v[32:35], v[92:95], v[56:59], v[32:35]
	v_add_u32_e32 v64, v46, v38
	v_bitop3_b32 v36, v169, v36, 4 bitop3:0x36
	v_lshl_add_u32 v40, v108, 7, s53
	v_mfma_f32_16x16x32_bf16 v[140:143], v[96:99], v[60:63], v[32:35]
	v_lshlrev_b32_e32 v36, 4, v36
	v_add_u32_e32 v39, v37, v38
	v_add_u32_e32 v41, v40, v38
	s_nop 0
	v_add_u32_e32 v32, v65, v38
	s_waitcnt lgkmcnt(0)
	ds_read_b128 v[116:119], v64 offset:16384
	ds_read_b128 v[104:107], v32 offset:16384
	v_mfma_f32_16x16x32_bf16 v[32:35], v[100:103], v[48:51], v[42:45]
	ds_read_b128 v[120:123], v39 offset:16384
	ds_read_b128 v[108:111], v39 offset:24576
	ds_read_b128 v[96:99], v39 offset:26624
	ds_read_b128 v[92:95], v39 offset:28672
	ds_read_b128 v[124:127], v41 offset:16384
	ds_read_b128 v[88:91], v39 offset:30720
	v_add_u32_e32 v37, v37, v36
	v_mfma_f32_16x16x32_bf16 v[32:35], v[112:115], v[52:55], v[32:35]
	v_add_u32_e32 v38, v40, v36
	v_mfma_f32_16x16x32_bf16 v[32:35], v[128:131], v[56:59], v[32:35]
	v_mfma_f32_16x16x32_bf16 v[128:131], v[170:173], v[60:63], v[32:35]
	s_nop 6
	v_add_u32_e32 v32, v46, v36
	v_add_u32_e32 v33, v65, v36
	ds_read_b128 v[84:87], v32 offset:16384
	ds_read_b128 v[80:83], v33 offset:16384
	ds_read_b128 v[100:103], v37 offset:16384
	ds_read_b128 v[76:79], v37 offset:24576
	ds_read_b128 v[72:75], v37 offset:26624
	ds_read_b128 v[68:71], v37 offset:28672
	ds_read_b128 v[112:115], v38 offset:16384
	ds_read_b128 v[64:67], v37 offset:30720
	v_sub_u32_e32 v32, v166, v47
	s_nop 0
	v_readfirstlane_b32 s53, v32
	s_cmp_gt_i32 s54, s53
	s_mov_b64 s[54:55], -1
	s_cbranch_scc1 .LBB0_212
	v_cndmask_b32_e64 v32, v229, v132, s[50:51]
	v_max_f32_e32 v33, v32, v32
	v_max_f32_e32 v35, 0xf149f2ca, v33
	v_cndmask_b32_e64 v33, v229, v133, s[50:51]
	v_cndmask_b32_e64 v34, v229, v134, s[50:51]
	v_max3_f32 v37, v35, v33, v34
	v_cndmask_b32_e64 v35, v229, v135, s[50:51]
	v_cndmask_b32_e64 v36, v229, v136, s[50:51]
	v_max3_f32 v39, v37, v35, v36
	v_cndmask_b32_e64 v37, v229, v137, s[50:51]
	v_cndmask_b32_e64 v38, v229, v138, s[50:51]
	v_max3_f32 v41, v39, v37, v38
	v_cndmask_b32_e64 v39, v229, v139, s[50:51]
	v_cndmask_b32_e64 v40, v229, v140, s[50:51]
	v_max3_f32 v43, v41, v39, v40
	v_cndmask_b32_e64 v41, v229, v141, s[50:51]
	v_cndmask_b32_e64 v42, v229, v142, s[50:51]
	v_max3_f32 v45, v43, v41, v42
	v_cndmask_b32_e64 v43, v229, v143, s[50:51]
	v_cndmask_b32_e64 v44, v229, v128, s[50:51]
	v_max3_f32 v47, v45, v43, v44
	v_cndmask_b32_e64 v45, v229, v129, s[50:51]
	v_cndmask_b32_e64 v46, v229, v130, s[50:51]
	v_max3_f32 v170, v47, v45, v46
	s_mov_b64 s[54:55], 0
